# P2 pool-unit rebalancing: the 48 workgroups that also own a sample unit do 2 pool units, their other 2 go to workgroups 48..143 as a fifth unit
# speedup vs baseline: 1.0411x; 1.0031x over previous
; #define LAS __attribute__((address_space(3)))
; __device__ __forceinline__ void mixer_phase(const Params& p, LAS unsigned char* lds) {
;     ...
;     const bf16_t* zb = (const bf16_t*)(p.ws + OFF_ZB);
;     bf16_t* mix = (bf16_t*)(p.ws + OFF_MIXB);
;     LAS float* P = (LAS float*)lds;
;     LAS bf16_t* Dm = (LAS bf16_t*)(lds + DM_OFF);
;     const int mt = wid & 3, nh = wid >> 2;
;     int gcur = -1; bf16x8 wb[4][4]; f32x4 scv[4];
;     ...
;     u32x4 pq[3];
;     ...
;     if (bx < 1024) POOL_PREFETCH(bx);
;     ...
;     for (int u = bx; u < 1024; u += G) {
;         const int tt = u >> 2, g = u & 3, b = tt >> 5, t0 = (tt & 31) * 64, grow0 = b * T + t0, w = 2 << g;
;         POOL_LOADW(g);
;         u32x4 cp[3];
; #pragma unroll
;         for (int i = 0; i < 3; ++i) cp[i] = pq[i];
;         if (u + G < 1024) POOL_PREFETCH(u + G);
.LBB0_287:
	v_lshrrev_b32_e32 v14, 4, v90
	v_and_b32_e32 v107, 15, v0
	s_and_b32 s52, s10, 3
	s_ashr_i32 s54, s10, 2
	s_andn2_b64 vcc, exec, s[4:5]
	v_lshlrev_b32_e32 v133, 1, v0
	v_and_b32_e32 v109, 3, v0
	v_lshlrev_b32_e32 v110, 3, v14
	v_lshlrev_b32_e32 v114, 5, v14
	v_lshlrev_b32_e32 v112, 4, v14
	s_cbranch_vccnz .LBB0_320
	s_mov_b32 s99, 0
	s_lshl_b32 s68, s54, 6
	v_and_b32_e32 v14, 24, v133
	v_lshlrev_b32_e32 v18, 3, v0
	v_and_b32_e32 v15, 0x78, v18
	v_or3_b32 v14, v14, v109, s68
	v_lshlrev_b32_e32 v116, 1, v15
	v_lshl_add_u32 v19, v15, 2, 0
	v_lshrrev_b32_e32 v15, 3, v0
	v_or_b32_e32 v16, 4, v14
	v_and_b32_e32 v138, 48, v15
	v_lshlrev_b32_e32 v21, 9, v15
	v_ashrrev_i32_e32 v15, 31, v14
	v_ashrrev_i32_e32 v17, 31, v16
	v_lshlrev_b64 v[120:121], 8, v[14:15]
	v_lshlrev_b64 v[122:123], 8, v[16:17]
	v_or_b32_e32 v16, 32, v14
	v_or_b32_e32 v14, 36, v14
	v_ashrrev_i32_e32 v15, 31, v14
	s_load_dwordx16 s[36:51], s[0:1], 0x40
	v_lshlrev_b64 v[126:127], 8, v[14:15]
	v_lshlrev_b32_e32 v15, 5, v0
	v_and_b32_e32 v15, 0x3e00, v15
	s_ashr_i32 s69, s68, 31
	v_or_b32_e32 v14, 0x200, v0
	v_add_u32_e32 v142, v19, v15
	s_movk_i32 s8, 0x1f80
	v_mov_b32_e32 v15, 0x1000
	v_lshrrev_b32_e32 v140, 4, v14
	v_or_b32_e32 v14, 0x400, v0
	s_movk_i32 s6, 0x4f0
	v_bitop3_b32 v15, v18, s8, v15 bitop3:0xc8
	s_lshl_b64 s[8:9], s[68:69], 2
	v_mov_b32_e32 v117, 0
	v_cmp_gt_u32_e64 s[6:7], s6, v14
	v_lshrrev_b32_e32 v141, 4, v14
	v_lshlrev_b32_e32 v14, 5, v14
	s_waitcnt lgkmcnt(0)
	s_add_u32 s8, s38, s8
	v_and_b32_e32 v14, 0xbe00, v14
	s_addc_u32 s9, s39, s9
	v_mov_b32_e32 v115, v117
	v_mov_b32_e32 v113, v117
	v_and_b32_e32 v20, 0x7f, v0
	v_lshl_add_u32 v143, v15, 2, v19
	v_add_u32_e32 v144, v19, v14
	v_lshl_add_u64 v[128:129], s[8:9], 0, v[114:115]
	v_lshl_add_u64 v[14:15], s[30:31], 0, v[112:113]
	s_mov_b64 s[8:9], 0x2d00000
	v_lshl_add_u64 v[118:119], s[64:65], 0, v[116:117]
	v_lshl_add_u64 v[130:131], v[14:15], 0, s[8:9]
	v_lshlrev_b32_e32 v116, 2, v20
	s_movk_i32 s8, 0x1e00
	v_or3_b32 v14, v21, v116, s8
	v_lshrrev_b32_e32 v132, 7, v0
	v_add_u32_e32 v113, 0, v14
	v_lshl_or_b32 v14, v132, 13, v116
	v_add_u32_e32 v14, 0, v14
	v_add_u32_e32 v145, 0x1e00, v14
	v_mul_u32_u24_e32 v14, 0x1100, v132
	v_lshl_or_b32 v14, v20, 1, v14
	v_add_u32_e32 v14, 0, v14
	v_lshl_or_b32 v139, s52, 4, v107
	s_movk_i32 s4, 0x110
	v_add_u32_e32 v146, 0x9e00, v14
	v_lshl_add_u32 v14, v0, 2, 0
	v_mad_u32_u24 v22, v139, s4, 0
	v_and_b32_e32 v23, 48, v0
	v_ashrrev_i32_e32 v17, 31, v16
	s_movk_i32 s4, 0x2f0
	v_add_u32_e32 v148, 0x8000, v14
	v_lshl_add_u64 v[14:15], s[28:29], 0, v[116:117]
	s_mov_b64 s[8:9], 0x4080000
	s_mov_b32 s71, 0
	v_lshlrev_b64 v[124:125], 8, v[16:17]
	v_cmp_gt_u32_e64 s[4:5], s4, v0
	v_add_u32_e32 v115, 0xfffff000, v113
	s_lshl_b32 s55, s2, 4
	s_lshl_b32 s56, s3, 4
	v_or_b32_e32 v147, 0xfffffe00, v0
	v_lshl_add_u64 v[134:135], v[14:15], 0, s[8:9]
	s_mov_b32 s53, -1
	s_movk_i32 s57, 0x7fff
	s_mov_b64 s[72:73], 0x2000
	s_movk_i32 s58, 0x57f
	v_add_u32_e32 v149, v22, v23
	v_lshlrev_b32_e32 v116, 1, v110
	s_mov_b32 s59, s2
	s_mov_b32 s77, s2
	s_and_b32 s78, s77, 3
	s_cmp_eq_u32 s78, s53
	s_cbranch_scc1 .LBB0_291
	s_branch .LBB0_290

; __device__ __forceinline__ void mixer_phase(const Params& p, LAS unsigned char* lds) {
;     ...
;     for (int u = bx; u < 1024; u += G) {
;         const int tt = u >> 2, g = u & 3, b = tt >> 5, t0 = (tt & 31) * 64, grow0 = b * T + t0, w = 2 << g;
;         POOL_LOADW(g);
;         u32x4 cp[3];
; #pragma unroll
;         for (int i = 0; i < 3; ++i) cp[i] = pq[i];
;         if (u + G < 1024) POOL_PREFETCH(u + G);
.LBB0_291:
	s_add_i32 s76, s77, s3
	s_cmp_lt_u32 s2, 48
	s_movk_i32 s98, 0x3ff
	s_cselect_b32 s98, 0x1ff, s98
	s_cmp_gt_i32 s76, s98
	s_cselect_b64 s[74:75], -1, 0
	s_sub_u32 s100, s2, 48
	s_cmp_lt_u32 s100, 0x60
	s_cbranch_scc0 .Lmy_p2std
	s_cmp_eq_u32 s99, 0
	s_cbranch_scc0 .Lmy_p2fin
	s_cmp_gt_i32 s76, 0x3ff
	s_cbranch_scc0 .Lmy_p2std
	s_mov_b32 s99, 1
	s_add_i32 s76, s2, 0x1d0
	s_cmp_lt_u32 s100, 48
	s_cbranch_scc1 .Lmy_p2set
	s_add_i32 s76, s2, 0x2a0
.Lmy_p2set:
	s_mov_b64 s[74:75], 0
	s_branch .Lmy_p2std
.Lmy_p2fin:
	s_mov_b64 s[74:75], -1
.Lmy_p2std:
	s_waitcnt vmcnt(0)
	v_mov_b64_e32 v[96:97], v[4:5]
	v_mov_b64_e32 v[100:101], v[8:9]
	s_and_b64 vcc, exec, s[74:75]
	v_mov_b32_e32 v105, v13
	v_mov_b32_e32 v104, v12
	v_mov_b32_e32 v103, v11
	v_mov_b32_e32 v102, v10
	v_mov_b64_e32 v[94:95], v[2:3]
	v_mov_b64_e32 v[98:99], v[6:7]
	s_cbranch_vccnz .LBB0_299
	s_lshl_b32 s8, s76, 4
	s_and_b32 s10, s8, 0x7c0
	s_add_i32 s10, s10, -15
	s_and_b32 s11, s8, 0xfffff800
	s_lshl_b32 s8, s76, 8
	v_mov_b32_e32 v96, v117
	v_mov_b32_e32 v97, v117
	s_and_b32 s70, s8, 0x300
	v_add_u32_e32 v102, s10, v111
	v_mov_b32_e32 v94, 0
	v_mov_b32_e32 v95, v117
	v_mov_b64_e32 v[100:101], v[96:97]
	v_lshl_add_u64 v[136:137], v[118:119], 0, s[70:71]
	v_cmp_lt_i32_e32 vcc, -1, v102
	v_mov_b64_e32 v[98:99], v[94:95]
	s_and_saveexec_b64 s[8:9], vcc
	s_cbranch_execz .LBB0_294
	v_add_u32_e32 v98, s11, v102
	v_ashrrev_i32_e32 v99, 31, v98
	v_lshlrev_b64 v[98:99], 12, v[98:99]
	v_lshl_add_u64 v[98:99], v[136:137], 0, v[98:99]
	global_load_dwordx4 v[98:101], v[98:99], off nt

; __device__ __forceinline__ void mixer_phase(const Params& p, LAS unsigned char* lds) {
;     ...
;     for (int u = bx; u < 1024; u += G) {
.LBB0_318:
	s_waitcnt lgkmcnt(0)
	s_barrier
	ds_read_b128 v[2:5], v149 offset:40448
	ds_read_b128 v[6:9], v149 offset:40512
	v_lshl_or_b32 v136, s11, 11, v139
	s_waitcnt lgkmcnt(1)
	v_mfma_f32_16x16x32_bf16 v[10:13], v[70:73], v[2:5], 0
	v_or_b32_e32 v136, s10, v136
	v_ashrrev_i32_e32 v137, 31, v136
	v_lshlrev_b64 v[136:137], 11, v[136:137]
	v_mfma_f32_16x16x32_bf16 v[150:153], v[74:77], v[2:5], 0
	v_lshl_add_u64 v[136:137], s[66:67], 0, v[136:137]
	v_lshl_add_u64 v[136:137], s[70:71], 1, v[136:137]
	v_lshl_add_u64 v[136:137], s[68:69], 1, v[136:137]
	v_mfma_f32_16x16x32_bf16 v[154:157], v[66:69], v[2:5], 0
	v_lshl_add_u64 v[136:137], v[136:137], 0, v[116:117]
	s_lshl_b32 s55, s76, 4
	s_mov_b32 s59, s76
	v_mfma_f32_16x16x32_bf16 v[2:5], v[62:65], v[2:5], 0
	s_and_b64 vcc, exec, s[74:75]
	s_waitcnt lgkmcnt(0)
	v_mfma_f32_16x16x32_bf16 v[10:13], v[58:61], v[6:9], v[10:13]
	v_mfma_f32_16x16x32_bf16 v[150:153], v[54:57], v[6:9], v[150:153]
	v_mfma_f32_16x16x32_bf16 v[154:157], v[50:53], v[6:9], v[154:157]
	v_mfma_f32_16x16x32_bf16 v[2:5], v[42:45], v[6:9], v[2:5]
	ds_read_b128 v[6:9], v149 offset:40576
	ds_read_b128 v[158:161], v149 offset:40640
	s_waitcnt lgkmcnt(1)
	v_mfma_f32_16x16x32_bf16 v[10:13], v[30:33], v[6:9], v[10:13]
	v_mfma_f32_16x16x32_bf16 v[150:153], v[46:49], v[6:9], v[150:153]
	s_waitcnt lgkmcnt(0)
	v_mfma_f32_16x16x32_bf16 v[10:13], v[26:29], v[158:161], v[10:13]
	v_mfma_f32_16x16x32_bf16 v[154:157], v[38:41], v[6:9], v[154:157]
	v_mfma_f32_16x16x32_bf16 v[150:153], v[22:25], v[158:161], v[150:153]
	s_nop 5
	v_mul_f32_e64 v12, v84, v12
	v_mul_f32_e64 v13, v85, v13
	v_pk_mul_f32 v[10:11], v[82:83], v[10:11]
	v_mfma_f32_16x16x32_bf16 v[2:5], v[34:37], v[6:9], v[2:5]
	v_cvt_pk_bf16_f32 v10, v10, v11
	v_cvt_pk_bf16_f32 v11, v12, v13
	v_mul_f32_e64 v162, v80, v152
	v_mul_f32_e64 v163, v81, v153
	v_pk_mul_f32 v[12:13], v[78:79], v[150:151]
	v_mfma_f32_16x16x32_bf16 v[150:153], v[18:21], v[158:161], v[154:157]
	v_cvt_pk_bf16_f32 v12, v12, v13
	v_cvt_pk_bf16_f32 v13, v162, v163
	global_store_dwordx4 v[136:137], v[10:13], off
	v_mfma_f32_16x16x32_bf16 v[2:5], v[14:17], v[158:161], v[2:5]
	s_nop 5
	v_mul_f32_e64 v6, v90, v150
	v_mul_f32_e64 v7, v91, v151
	v_pk_mul_f32 v[10:11], v[92:93], v[152:153]
	v_cvt_pk_bf16_f32 v6, v6, v7
	v_pk_mul_f32 v[4:5], v[88:89], v[4:5]
	v_cvt_pk_bf16_f32 v7, v10, v11
	v_pk_mul_f32 v[2:3], v[86:87], v[2:3]
	v_cvt_pk_bf16_f32 v9, v4, v5
	s_nop 0
	v_cvt_pk_bf16_f32 v8, v2, v3
	global_store_dwordx4 v[136:137], v[6:9], off offset:64
	s_cbranch_vccz .LBB0_289
	s_cmp_gt_i32 s2, 47
	s_cbranch_scc1 .LBB0_333
	s_branch .LBB0_321
